# grid barrier: waiters poll the top-level arrival counter (done at (barrier index + 1) x number of XCDs) instead of a generation word bumped by the last leader afterwards
# baseline (speedup 1.0000x reference)
; __device__ __forceinline__ unsigned xb_ld(unsigned* p)              { return __hip_atomic_load(p, __ATOMIC_RELAXED, __HIP_MEMORY_SCOPE_AGENT); }
; __device__ __forceinline__ unsigned xb_add(unsigned* p, unsigned v) { return __hip_atomic_fetch_add(p, v, __ATOMIC_RELAXED, __HIP_MEMORY_SCOPE_AGENT); }
; #define XB_SPIN(cond, bar) do { unsigned _sp = 0; while (cond) { __builtin_amdgcn_s_sleep(1); \
;     if ((++_sp & 255u) == 0u) { if (xb_ld(&(bar)[XB_TMO])) break; if (_sp > XB_SPIN_CAP) { atomicAdd(&(bar)[XB_TMO], 1u); break; } } } } while (0)
; __device__ __forceinline__ void xcd_barrier(const XcdBarrier& b, const int tid0) {
;     ...
;         const unsigned old = xb_add(&bar[XB_XSUB(b.x)], 1u);
;         const unsigned gen = old / nloc;
;         if (old + 1u == (gen + 1u) * nloc) {
;     ...
;         } else {
;             XB_SPIN(xb_ld(&bar[XB_XGEN(b.x)]) == gen, bar);
;             __builtin_amdgcn_fence(__ATOMIC_ACQUIRE, "agent");
.LBB0_4100:
	s_lshl_b32 s2, s52, 8
	s_add_u32 s6, s4, s2
	s_addc_u32 s7, s5, 0
	v_mov_b32_e32 v1, 0x1000
	v_mov_b32_e32 v3, 1
	global_atomic_add v3, v1, v3, s[6:7] offset:1024 sc0
	v_cvt_f32_u32_e32 v1, v2
	v_sub_u32_e32 v4, 0, v2
	v_rcp_iflag_f32_e32 v1, v1
	s_nop 0
	v_mul_f32_e32 v1, 0x4f7ffffe, v1
	v_cvt_u32_f32_e32 v1, v1
	v_mul_lo_u32 v4, v4, v1
	v_mul_hi_u32 v4, v1, v4
	v_add_u32_e32 v1, v1, v4
	s_waitcnt vmcnt(0)
	v_mul_hi_u32 v1, v3, v1
	v_mul_lo_u32 v4, v1, v2
	v_sub_u32_e32 v4, v3, v4
	v_add_u32_e32 v5, 1, v1
	v_cmp_ge_u32_e32 vcc, v4, v2
	v_add_u32_e32 v3, 1, v3
	s_nop 0
	v_cndmask_b32_e32 v1, v1, v5, vcc
	v_sub_u32_e32 v5, v4, v2
	v_cndmask_b32_e32 v4, v4, v5, vcc
	v_add_u32_e32 v5, 1, v1
	v_cmp_ge_u32_e32 vcc, v4, v2
	s_nop 1
	v_cndmask_b32_e32 v1, v1, v5, vcc
	v_mul_lo_u32 v4, v2, v1
	v_add_u32_e32 v2, v4, v2
	v_cmp_ne_u32_e32 vcc, v3, v2
	s_and_saveexec_b64 s[2:3], vcc
	s_xor_b64 s[8:9], exec, s[2:3]
	s_cbranch_execz .LBB0_4114
	s_waitcnt lgkmcnt(0)
	v_add_u32_e32 v5, 1, v1
	v_mul_lo_u32 v5, v5, v0
	v_mov_b32_e32 v0, 0x3000
	global_load_dword v0, v0, s[4:5] offset:1024 sc1
	s_add_u32 s12, s4, 0x3400
	s_addc_u32 s13, s5, 0
	s_waitcnt vmcnt(0)
	v_cmp_lt_u32_e32 vcc, v0, v5
	s_and_saveexec_b64 s[10:11], vcc
	s_cbranch_execz .LBB0_4113
	s_mov_b32 s2, 1
	s_mov_b64 s[14:15], 0
	v_mov_b32_e32 v0, 0
	s_branch .LBB0_4104

; __device__ __forceinline__ unsigned xb_ld(unsigned* p)              { return __hip_atomic_load(p, __ATOMIC_RELAXED, __HIP_MEMORY_SCOPE_AGENT); }
; #define XB_SPIN(cond, bar) do { unsigned _sp = 0; while (cond) { __builtin_amdgcn_s_sleep(1); \
;     if ((++_sp & 255u) == 0u) { if (xb_ld(&(bar)[XB_TMO])) break; if (_sp > XB_SPIN_CAP) { atomicAdd(&(bar)[XB_TMO], 1u); break; } } } } while (0)
; __device__ __forceinline__ void xcd_barrier(const XcdBarrier& b, const int tid0) {
;     ...
;             XB_SPIN(xb_ld(&bar[XB_XGEN(b.x)]) == gen, bar);
.LBB0_4106:
	global_load_dword v2, v0, s[12:13] sc1
	s_add_i32 s2, s2, 1
	s_mov_b64 s[22:23], -1
	s_waitcnt vmcnt(0)
	v_cmp_ge_u32_e32 vcc, v2, v5
	s_orn2_b64 s[18:19], vcc, exec
	s_branch .LBB0_4103

; __device__ __forceinline__ unsigned xb_ld(unsigned* p)              { return __hip_atomic_load(p, __ATOMIC_RELAXED, __HIP_MEMORY_SCOPE_AGENT); }
; __device__ __forceinline__ unsigned xb_add(unsigned* p, unsigned v) { return __hip_atomic_fetch_add(p, v, __ATOMIC_RELAXED, __HIP_MEMORY_SCOPE_AGENT); }
; #define XB_SPIN(cond, bar) do { unsigned _sp = 0; while (cond) { __builtin_amdgcn_s_sleep(1); \
;     if ((++_sp & 255u) == 0u) { if (xb_ld(&(bar)[XB_TMO])) break; if (_sp > XB_SPIN_CAP) { atomicAdd(&(bar)[XB_TMO], 1u); break; } } } } while (0)
; __device__ __forceinline__ void xcd_barrier(const XcdBarrier& b, const int tid0) {
;     ...
;             const unsigned og = xb_add(&bar[XB_TOP], 1u);
;             const unsigned tg = og / nx;
;             if (og + 1u == (tg + 1u) * nx) xb_add(&bar[XB_TOPGEN], 1u);
;             else XB_SPIN(xb_ld(&bar[XB_TOPGEN]) == tg, bar);
.LBB0_4117:
	s_or_b64 exec, exec, s[8:9]
	v_cvt_f32_u32_e32 v3, v0
	s_waitcnt vmcnt(0)
	v_readfirstlane_b32 s2, v2
	s_add_u32 s10, s4, 0x3500
	s_addc_u32 s11, s5, 0
	v_rcp_iflag_f32_e32 v3, v3
	v_add_u32_e32 v1, s2, v1
	v_add_u32_e32 v4, 1, v1
	s_mov_b64 s[2:3], -1
	v_mul_f32_e32 v2, 0x4f7ffffe, v3
	v_cvt_u32_f32_e32 v2, v2
	v_sub_u32_e32 v3, 0, v0
	v_mul_lo_u32 v3, v3, v2
	v_mul_hi_u32 v3, v2, v3
	v_add_u32_e32 v2, v2, v3
	v_mul_hi_u32 v2, v1, v2
	v_mul_lo_u32 v3, v2, v0
	v_sub_u32_e32 v1, v1, v3
	v_add_u32_e32 v5, 1, v2
	v_cmp_ge_u32_e32 vcc, v1, v0
	v_sub_u32_e32 v3, v1, v0
	s_nop 0
	v_cndmask_b32_e32 v2, v2, v5, vcc
	v_cndmask_b32_e32 v1, v1, v3, vcc
	v_add_u32_e32 v3, 1, v2
	v_cmp_ge_u32_e32 vcc, v1, v0
	s_nop 1
	v_cndmask_b32_e32 v2, v2, v3, vcc
	v_mul_lo_u32 v1, v0, v2
	v_add_u32_e32 v0, v1, v0
	v_cmp_ne_u32_e32 vcc, v4, v0
	v_mov_b32_e32 v2, v0
	v_mov_b64_e32 v[0:1], s[10:11]
	s_and_saveexec_b64 s[8:9], vcc
	s_cbranch_execz .LBB0_4129
	v_mov_b32_e32 v0, 0
	s_add_u32 s100, s4, 0x3400
	s_addc_u32 s101, s5, 0
	global_load_dword v1, v0, s[100:101] sc1
	s_mov_b64 s[2:3], 0
	s_waitcnt vmcnt(0)
	v_cmp_lt_u32_e32 vcc, v1, v2
	s_and_saveexec_b64 s[14:15], vcc
	s_cbranch_execz .LBB0_4128
	s_add_u32 s12, s4, 0x200
	s_addc_u32 s13, s5, 0
	s_mov_b32 s20, 1
	s_mov_b64 s[4:5], 0
	s_branch .LBB0_4121

; __device__ __forceinline__ unsigned xb_ld(unsigned* p)              { return __hip_atomic_load(p, __ATOMIC_RELAXED, __HIP_MEMORY_SCOPE_AGENT); }
; #define XB_SPIN(cond, bar) do { unsigned _sp = 0; while (cond) { __builtin_amdgcn_s_sleep(1); \
;     if ((++_sp & 255u) == 0u) { if (xb_ld(&(bar)[XB_TMO])) break; if (_sp > XB_SPIN_CAP) { atomicAdd(&(bar)[XB_TMO], 1u); break; } } } } while (0)
; __device__ __forceinline__ void xcd_barrier(const XcdBarrier& b, const int tid0) {
;     ...
;             else XB_SPIN(xb_ld(&bar[XB_TOPGEN]) == tg, bar);
.LBB0_4123:
	global_load_dword v1, v0, s[100:101] sc1
	s_add_i32 s20, s20, 1
	s_mov_b64 s[18:19], -1
	s_waitcnt vmcnt(0)
	v_cmp_ge_u32_e32 vcc, v1, v2
	s_orn2_b64 s[2:3], vcc, exec
	s_branch .LBB0_4120

; __device__ __forceinline__ unsigned xb_ld(unsigned* p)              { return __hip_atomic_load(p, __ATOMIC_RELAXED, __HIP_MEMORY_SCOPE_AGENT); }
; __device__ __forceinline__ unsigned xb_add(unsigned* p, unsigned v) { return __hip_atomic_fetch_add(p, v, __ATOMIC_RELAXED, __HIP_MEMORY_SCOPE_AGENT); }
; #define XB_SPIN(cond, bar) do { unsigned _sp = 0; while (cond) { __builtin_amdgcn_s_sleep(1); \
;     if ((++_sp & 255u) == 0u) { if (xb_ld(&(bar)[XB_TMO])) break; if (_sp > XB_SPIN_CAP) { atomicAdd(&(bar)[XB_TMO], 1u); break; } } } } while (0)
; __device__ __forceinline__ void xcd_barrier(const XcdBarrier& b, const int tid0) {
;     ...
;         const unsigned old = xb_add(&bar[XB_XSUB(b.x)], 1u);
;         const unsigned gen = old / nloc;
;         if (old + 1u == (gen + 1u) * nloc) {
;     ...
;         } else {
;             XB_SPIN(xb_ld(&bar[XB_XGEN(b.x)]) == gen, bar);
;             __builtin_amdgcn_fence(__ATOMIC_ACQUIRE, "agent");
.LBB0_4397:
	v_readlane_b32 s6, v254, 1
	s_lshl_b32 s6, s6, 2
	s_add_u32 s6, s4, s6
	s_addc_u32 s7, s5, 0
	v_mov_b32_e32 v1, 0x1000
	v_mov_b32_e32 v3, 1
	global_atomic_add v3, v1, v3, s[6:7] offset:1024 sc0
	v_cvt_f32_u32_e32 v1, v2
	v_sub_u32_e32 v4, 0, v2
	v_rcp_iflag_f32_e32 v1, v1
	s_nop 0
	v_mul_f32_e32 v1, 0x4f7ffffe, v1
	v_cvt_u32_f32_e32 v1, v1
	v_mul_lo_u32 v4, v4, v1
	v_mul_hi_u32 v4, v1, v4
	v_add_u32_e32 v1, v1, v4
	s_waitcnt vmcnt(0)
	v_mul_hi_u32 v1, v3, v1
	v_mul_lo_u32 v4, v1, v2
	v_sub_u32_e32 v4, v3, v4
	v_add_u32_e32 v5, 1, v1
	v_cmp_ge_u32_e32 vcc, v4, v2
	v_add_u32_e32 v3, 1, v3
	s_nop 0
	v_cndmask_b32_e32 v1, v1, v5, vcc
	v_sub_u32_e32 v5, v4, v2
	v_cndmask_b32_e32 v4, v4, v5, vcc
	v_add_u32_e32 v5, 1, v1
	v_cmp_ge_u32_e32 vcc, v4, v2
	s_nop 1
	v_cndmask_b32_e32 v1, v1, v5, vcc
	v_mul_lo_u32 v4, v2, v1
	v_add_u32_e32 v2, v4, v2
	v_cmp_ne_u32_e32 vcc, v3, v2
	s_and_saveexec_b64 s[10:11], vcc
	s_xor_b64 s[10:11], exec, s[10:11]
	s_cbranch_execz .LBB0_4411
	s_waitcnt lgkmcnt(0)
	v_add_u32_e32 v5, 1, v1
	v_mul_lo_u32 v5, v5, v0
	v_mov_b32_e32 v0, 0x3000
	global_load_dword v0, v0, s[4:5] offset:1024 sc1
	s_add_u32 s16, s4, 0x3400
	s_addc_u32 s17, s5, 0
	s_waitcnt vmcnt(0)
	v_cmp_lt_u32_e32 vcc, v0, v5
	s_and_saveexec_b64 s[12:13], vcc
	s_cbranch_execz .LBB0_4410
	s_mov_b32 s14, 1
	s_mov_b64 s[18:19], 0
	s_branch .LBB0_4401

; __device__ __forceinline__ unsigned xb_ld(unsigned* p)              { return __hip_atomic_load(p, __ATOMIC_RELAXED, __HIP_MEMORY_SCOPE_AGENT); }
; #define XB_SPIN(cond, bar) do { unsigned _sp = 0; while (cond) { __builtin_amdgcn_s_sleep(1); \
;     if ((++_sp & 255u) == 0u) { if (xb_ld(&(bar)[XB_TMO])) break; if (_sp > XB_SPIN_CAP) { atomicAdd(&(bar)[XB_TMO], 1u); break; } } } } while (0)
; __device__ __forceinline__ void xcd_barrier(const XcdBarrier& b, const int tid0) {
;     ...
;             XB_SPIN(xb_ld(&bar[XB_XGEN(b.x)]) == gen, bar);
.LBB0_4403:
	global_load_dword v0, v32, s[16:17] sc1
	s_add_i32 s14, s14, 1
	s_mov_b64 s[34:35], -1
	s_waitcnt vmcnt(0)
	v_cmp_ge_u32_e32 vcc, v0, v5
	s_orn2_b64 s[30:31], vcc, exec
	s_branch .LBB0_4400

; __device__ __forceinline__ unsigned xb_ld(unsigned* p)              { return __hip_atomic_load(p, __ATOMIC_RELAXED, __HIP_MEMORY_SCOPE_AGENT); }
; __device__ __forceinline__ unsigned xb_add(unsigned* p, unsigned v) { return __hip_atomic_fetch_add(p, v, __ATOMIC_RELAXED, __HIP_MEMORY_SCOPE_AGENT); }
; #define XB_SPIN(cond, bar) do { unsigned _sp = 0; while (cond) { __builtin_amdgcn_s_sleep(1); \
;     if ((++_sp & 255u) == 0u) { if (xb_ld(&(bar)[XB_TMO])) break; if (_sp > XB_SPIN_CAP) { atomicAdd(&(bar)[XB_TMO], 1u); break; } } } } while (0)
; __device__ __forceinline__ void xcd_barrier(const XcdBarrier& b, const int tid0) {
;     ...
;             const unsigned og = xb_add(&bar[XB_TOP], 1u);
;             const unsigned tg = og / nx;
;             if (og + 1u == (tg + 1u) * nx) xb_add(&bar[XB_TOPGEN], 1u);
;             else XB_SPIN(xb_ld(&bar[XB_TOPGEN]) == tg, bar);
.LBB0_4414:
	s_or_b64 exec, exec, s[12:13]
	s_waitcnt vmcnt(0)
	v_readfirstlane_b32 s10, v2
	v_cvt_f32_u32_e32 v2, v0
	v_sub_u32_e32 v3, 0, v0
	v_add_u32_e32 v1, s10, v1
	s_add_u32 s10, s4, 0x3500
	v_rcp_iflag_f32_e32 v2, v2
	s_addc_u32 s11, s5, 0
	s_mov_b64 s[14:15], -1
	v_mul_f32_e32 v2, 0x4f7ffffe, v2
	v_cvt_u32_f32_e32 v2, v2
	v_mul_lo_u32 v3, v3, v2
	v_mul_hi_u32 v3, v2, v3
	v_add_u32_e32 v2, v2, v3
	v_mul_hi_u32 v2, v1, v2
	v_mul_lo_u32 v3, v2, v0
	v_sub_u32_e32 v3, v1, v3
	v_cmp_ge_u32_e32 vcc, v3, v0
	v_add_u32_e32 v4, 1, v2
	v_add_u32_e32 v1, 1, v1
	v_cndmask_b32_e32 v2, v2, v4, vcc
	v_sub_u32_e32 v4, v3, v0
	v_cndmask_b32_e32 v3, v3, v4, vcc
	v_cmp_ge_u32_e32 vcc, v3, v0
	v_add_u32_e32 v3, 1, v2
	s_nop 0
	v_cndmask_b32_e32 v2, v2, v3, vcc
	v_mul_lo_u32 v3, v0, v2
	v_add_u32_e32 v0, v3, v0
	v_cmp_ne_u32_e32 vcc, v1, v0
	v_mov_b32_e32 v2, v0
	v_mov_b64_e32 v[0:1], s[10:11]
	s_and_saveexec_b64 s[12:13], vcc
	s_cbranch_execz .LBB0_4426
	s_add_u32 s100, s4, 0x3400
	s_addc_u32 s101, s5, 0
	global_load_dword v0, v32, s[100:101] sc1
	s_mov_b64 s[14:15], 0
	s_waitcnt vmcnt(0)
	v_cmp_lt_u32_e32 vcc, v0, v2
	s_and_saveexec_b64 s[18:19], vcc
	s_cbranch_execz .LBB0_4425
	s_add_u32 s16, s4, 0x200
	s_addc_u32 s17, s5, 0
	s_mov_b32 s14, 1
	s_mov_b64 s[4:5], 0
	s_branch .LBB0_4418

; __device__ __forceinline__ unsigned xb_ld(unsigned* p)              { return __hip_atomic_load(p, __ATOMIC_RELAXED, __HIP_MEMORY_SCOPE_AGENT); }
; #define XB_SPIN(cond, bar) do { unsigned _sp = 0; while (cond) { __builtin_amdgcn_s_sleep(1); \
;     if ((++_sp & 255u) == 0u) { if (xb_ld(&(bar)[XB_TMO])) break; if (_sp > XB_SPIN_CAP) { atomicAdd(&(bar)[XB_TMO], 1u); break; } } } } while (0)
; __device__ __forceinline__ void xcd_barrier(const XcdBarrier& b, const int tid0) {
;     ...
;             else XB_SPIN(xb_ld(&bar[XB_TOPGEN]) == tg, bar);
.LBB0_4420:
	global_load_dword v0, v32, s[100:101] sc1
	s_add_i32 s14, s14, 1
	s_mov_b64 s[34:35], -1
	s_waitcnt vmcnt(0)
	v_cmp_ge_u32_e32 vcc, v0, v2
	s_orn2_b64 s[30:31], vcc, exec
	s_branch .LBB0_4417

; __device__ __forceinline__ unsigned xb_ld(unsigned* p)              { return __hip_atomic_load(p, __ATOMIC_RELAXED, __HIP_MEMORY_SCOPE_AGENT); }
; __device__ __forceinline__ unsigned xb_add(unsigned* p, unsigned v) { return __hip_atomic_fetch_add(p, v, __ATOMIC_RELAXED, __HIP_MEMORY_SCOPE_AGENT); }
; #define XB_SPIN(cond, bar) do { unsigned _sp = 0; while (cond) { __builtin_amdgcn_s_sleep(1); \
;     if ((++_sp & 255u) == 0u) { if (xb_ld(&(bar)[XB_TMO])) break; if (_sp > XB_SPIN_CAP) { atomicAdd(&(bar)[XB_TMO], 1u); break; } } } } while (0)
; __device__ __forceinline__ void xcd_barrier(const XcdBarrier& b, const int tid0) {
;     ...
;         const unsigned old = xb_add(&bar[XB_XSUB(b.x)], 1u);
;         const unsigned gen = old / nloc;
;         if (old + 1u == (gen + 1u) * nloc) {
;     ...
;         } else {
;             XB_SPIN(xb_ld(&bar[XB_XGEN(b.x)]) == gen, bar);
;             __builtin_amdgcn_fence(__ATOMIC_ACQUIRE, "agent");
.LBB0_4769:
	v_readlane_b32 s6, v254, 1
	s_lshl_b32 s6, s6, 2
	s_add_u32 s6, s4, s6
	s_addc_u32 s7, s5, 0
	v_mov_b32_e32 v1, 0x1000
	v_mov_b32_e32 v3, 1
	global_atomic_add v3, v1, v3, s[6:7] offset:1024 sc0
	v_cvt_f32_u32_e32 v1, v2
	v_sub_u32_e32 v4, 0, v2
	v_rcp_iflag_f32_e32 v1, v1
	s_nop 0
	v_mul_f32_e32 v1, 0x4f7ffffe, v1
	v_cvt_u32_f32_e32 v1, v1
	v_mul_lo_u32 v4, v4, v1
	v_mul_hi_u32 v4, v1, v4
	v_add_u32_e32 v1, v1, v4
	s_waitcnt vmcnt(0)
	v_mul_hi_u32 v1, v3, v1
	v_mul_lo_u32 v4, v1, v2
	v_sub_u32_e32 v4, v3, v4
	v_add_u32_e32 v5, 1, v1
	v_cmp_ge_u32_e32 vcc, v4, v2
	v_add_u32_e32 v3, 1, v3
	s_nop 0
	v_cndmask_b32_e32 v1, v1, v5, vcc
	v_sub_u32_e32 v5, v4, v2
	v_cndmask_b32_e32 v4, v4, v5, vcc
	v_add_u32_e32 v5, 1, v1
	v_cmp_ge_u32_e32 vcc, v4, v2
	s_nop 1
	v_cndmask_b32_e32 v1, v1, v5, vcc
	v_mul_lo_u32 v4, v2, v1
	v_add_u32_e32 v2, v4, v2
	v_cmp_ne_u32_e32 vcc, v3, v2
	s_and_saveexec_b64 s[8:9], vcc
	s_xor_b64 s[8:9], exec, s[8:9]
	s_cbranch_execz .LBB0_4783
	s_waitcnt lgkmcnt(0)
	v_add_u32_e32 v5, 1, v1
	v_mul_lo_u32 v5, v5, v0
	v_mov_b32_e32 v0, 0x3000
	global_load_dword v0, v0, s[4:5] offset:1024 sc1
	s_add_u32 s12, s4, 0x3400
	s_addc_u32 s13, s5, 0
	s_waitcnt vmcnt(0)
	v_cmp_lt_u32_e32 vcc, v0, v5
	s_and_saveexec_b64 s[10:11], vcc
	s_cbranch_execz .LBB0_4782
	s_mov_b32 s14, 1
	s_mov_b64 s[16:17], 0
	s_branch .LBB0_4773

; __device__ __forceinline__ unsigned xb_ld(unsigned* p)              { return __hip_atomic_load(p, __ATOMIC_RELAXED, __HIP_MEMORY_SCOPE_AGENT); }
; #define XB_SPIN(cond, bar) do { unsigned _sp = 0; while (cond) { __builtin_amdgcn_s_sleep(1); \
;     if ((++_sp & 255u) == 0u) { if (xb_ld(&(bar)[XB_TMO])) break; if (_sp > XB_SPIN_CAP) { atomicAdd(&(bar)[XB_TMO], 1u); break; } } } } while (0)
; __device__ __forceinline__ void xcd_barrier(const XcdBarrier& b, const int tid0) {
;     ...
;             else XB_SPIN(xb_ld(&bar[XB_TOPGEN]) == tg, bar);
.LBB0_4775:
	global_load_dword v0, v32, s[12:13] sc1
	s_add_i32 s14, s14, 1
	s_mov_b64 s[30:31], -1
	s_waitcnt vmcnt(0)
	v_cmp_ge_u32_e32 vcc, v0, v5
	s_orn2_b64 s[28:29], vcc, exec
	s_branch .LBB0_4772

; __device__ __forceinline__ unsigned xb_ld(unsigned* p)              { return __hip_atomic_load(p, __ATOMIC_RELAXED, __HIP_MEMORY_SCOPE_AGENT); }
; __device__ __forceinline__ unsigned xb_add(unsigned* p, unsigned v) { return __hip_atomic_fetch_add(p, v, __ATOMIC_RELAXED, __HIP_MEMORY_SCOPE_AGENT); }
; #define XB_SPIN(cond, bar) do { unsigned _sp = 0; while (cond) { __builtin_amdgcn_s_sleep(1); \
;     if ((++_sp & 255u) == 0u) { if (xb_ld(&(bar)[XB_TMO])) break; if (_sp > XB_SPIN_CAP) { atomicAdd(&(bar)[XB_TMO], 1u); break; } } } } while (0)
; __device__ __forceinline__ void xcd_barrier(const XcdBarrier& b, const int tid0) {
;     ...
;         const unsigned old = xb_add(&bar[XB_XSUB(b.x)], 1u);
;         const unsigned gen = old / nloc;
;         if (old + 1u == (gen + 1u) * nloc) {
;             __builtin_amdgcn_fence(__ATOMIC_RELEASE, "agent");
;             asm volatile("s_waitcnt vmcnt(0)" ::: "memory");
;             const unsigned og = xb_add(&bar[XB_TOP], 1u);
;             const unsigned tg = og / nx;
;             if (og + 1u == (tg + 1u) * nx) xb_add(&bar[XB_TOPGEN], 1u);
;             else XB_SPIN(xb_ld(&bar[XB_TOPGEN]) == tg, bar);
.LBB0_4786:
	s_or_b64 exec, exec, s[10:11]
	s_waitcnt vmcnt(0)
	v_readfirstlane_b32 s8, v2
	v_cvt_f32_u32_e32 v2, v0
	v_sub_u32_e32 v3, 0, v0
	v_add_u32_e32 v1, s8, v1
	s_add_u32 s8, s4, 0x3500
	v_rcp_iflag_f32_e32 v2, v2
	s_addc_u32 s9, s5, 0
	s_mov_b64 s[12:13], -1
	v_mul_f32_e32 v2, 0x4f7ffffe, v2
	v_cvt_u32_f32_e32 v2, v2
	v_mul_lo_u32 v3, v3, v2
	v_mul_hi_u32 v3, v2, v3
	v_add_u32_e32 v2, v2, v3
	v_mul_hi_u32 v2, v1, v2
	v_mul_lo_u32 v3, v2, v0
	v_sub_u32_e32 v3, v1, v3
	v_cmp_ge_u32_e32 vcc, v3, v0
	v_add_u32_e32 v4, 1, v2
	v_add_u32_e32 v1, 1, v1
	v_cndmask_b32_e32 v2, v2, v4, vcc
	v_sub_u32_e32 v4, v3, v0
	v_cndmask_b32_e32 v3, v3, v4, vcc
	v_cmp_ge_u32_e32 vcc, v3, v0
	v_add_u32_e32 v3, 1, v2
	s_nop 0
	v_cndmask_b32_e32 v2, v2, v3, vcc
	v_mul_lo_u32 v3, v0, v2
	v_add_u32_e32 v0, v3, v0
	v_cmp_ne_u32_e32 vcc, v1, v0
	v_mov_b32_e32 v2, v0
	v_mov_b64_e32 v[0:1], s[8:9]
	s_and_saveexec_b64 s[10:11], vcc
	s_cbranch_execz .LBB0_4798
	s_add_u32 s100, s4, 0x3400
	s_addc_u32 s101, s5, 0
	global_load_dword v0, v32, s[100:101] sc1
	s_mov_b64 s[14:15], 0
	s_waitcnt vmcnt(0)
	v_cmp_lt_u32_e32 vcc, v0, v2
	s_and_saveexec_b64 s[16:17], vcc
	s_cbranch_execz .LBB0_4797
	s_add_u32 s12, s4, 0x200
	s_addc_u32 s13, s5, 0
	s_mov_b32 s14, 1
	s_mov_b64 s[4:5], 0
	s_branch .LBB0_4790

; __device__ __forceinline__ unsigned xb_ld(unsigned* p)              { return __hip_atomic_load(p, __ATOMIC_RELAXED, __HIP_MEMORY_SCOPE_AGENT); }
; #define XB_SPIN(cond, bar) do { unsigned _sp = 0; while (cond) { __builtin_amdgcn_s_sleep(1); \
;     if ((++_sp & 255u) == 0u) { if (xb_ld(&(bar)[XB_TMO])) break; if (_sp > XB_SPIN_CAP) { atomicAdd(&(bar)[XB_TMO], 1u); break; } } } } while (0)
; __device__ __forceinline__ void xcd_barrier(const XcdBarrier& b, const int tid0) {
;     ...
;             else XB_SPIN(xb_ld(&bar[XB_TOPGEN]) == tg, bar);
.LBB0_4792:
	global_load_dword v0, v32, s[100:101] sc1
	s_add_i32 s14, s14, 1
	s_mov_b64 s[30:31], -1
	s_waitcnt vmcnt(0)
	v_cmp_ge_u32_e32 vcc, v0, v2
	s_orn2_b64 s[28:29], vcc, exec
	s_branch .LBB0_4789
